# code placement: 64-byte aligned heads of the attention x6 loops and every GEMM K-loop
# baseline (speedup 1.0000x reference)
; #define PG8_STAGE(bufoff, gbase, voff) do { _Pragma("unroll") for (int _i = 0; _i < 2; ++_i) \
;         __builtin_amdgcn_global_load_lds((const unsigned*)((const char*)(gbase) + (voff)[_i]), (LAS unsigned*)(lds + (bufoff) + ldsw + _i * 8192), 16, 0, 0); } while (0)
; #define PG8_LDA(dst, b, h) do { _Pragma("unroll") for (int m = 0; m < 4; ++m) _Pragma("unroll") for (int k = 0; k < 2; ++k) dst[m][k] = *(const LAS bf16x8*)(lds + PG8_SA(b, h) + aoff + m * 2048 + k * 1024); } while (0)
; #define PG8_LDB(dst, b, h) do { _Pragma("unroll") for (int n = 0; n < 2; ++n) _Pragma("unroll") for (int k = 0; k < 2; ++k) dst[n][k] = *(const LAS bf16x8*)(lds + PG8_SB(b, h) + boff + n * 2048 + k * 1024); } while (0)
; #define PG8_SCHED __builtin_amdgcn_sched_barrier(0)
; template <class Epi, bool BSEL = false>
; __device__ __forceinline__ void gemm_phase(LAS unsigned char* lds, const Gemm g, const Order& S, const Epi& E, const int tid) {
;     ...
;         const bool has_next = S.next(ui + 1, nxt);
;         const char* nA = has_next ? nxt.a : cA; const char* nB = has_next ? nxt.b : cB;
;         const bool nP = has_next ? (BSEL && nxt.kind == 3) : cP; const size_t nhB = nP ? hstepBp : hstepBn;
;         for (int t = 0; t < nt; t += 2) {
;             const bool last = (t == nt - 2);
;             const char* a1 = cA + (size_t)(t + 1) * kstep;
;             const char* a2 = last ? nA : cA + (size_t)(t + 2) * kstep; const char* b2 = last ? nB : cB + (size_t)(t + 2) * kstep;
;             const char* a3 = a2 + kstep; const char* b3 = b2 + kstep;
;             const bool p2 = last ? nP : cP; const size_t h2 = last ? nhB : chB;
;             PG8_LDB(B0, 0, 0); PG8_LDB(B1, 0, 1); PG8_SCHED; PG8_LDA(At, 0, 0); PG8_STAGE(PG8_SA(1, 1), a1 + hstepA, voffA);
.LBB0_323:
	s_xor_b64 s[30:31], s[36:37], -1
	s_add_u32 s25, s34, 0x100
	s_addc_u32 s51, s35, 0
	s_and_b64 s[2:3], s[36:37], exec
	s_cselect_b32 s52, s27, s9
	s_cselect_b32 s53, s26, s8
	s_cselect_b32 s54, s29, s35
	s_cselect_b32 s55, s28, s34
	v_lshl_add_u64 v[142:143], s[8:9], 0, v[136:137]
	v_lshl_add_u64 v[144:145], s[8:9], 0, v[138:139]
	s_mov_b32 s56, -2
	.p2align 6

;     __device__ __forceinline__ bool next(int i, Unit& u) const {
;         const long L = (long)i * G + c; if (L >= total) return false;
;         int w = (int)L; { const int q = total / 8, r = total % 8, xcd = w % 8, off = w / 8; w = (xcd < r ? xcd * (q + 1) : r * (q + 1) + (xcd - r) * q) + off; }
.LBB0_437:
	s_ashr_i32 s1, s1, 3
	s_add_i32 s1, s35, s1
	s_cmpk_gt_i32 s1, 0xff
	s_cbranch_scc1 .LBB0_439
	.p2align 6

; #define PG8_STAGE(bufoff, gbase, voff) do { _Pragma("unroll") for (int _i = 0; _i < 2; ++_i) \
;         __builtin_amdgcn_global_load_lds((const unsigned*)((const char*)(gbase) + (voff)[_i]), (LAS unsigned*)(lds + (bufoff) + ldsw + _i * 8192), 16, 0, 0); } while (0)
; #define PG8_LDA(dst, b, h) do { _Pragma("unroll") for (int m = 0; m < 4; ++m) _Pragma("unroll") for (int k = 0; k < 2; ++k) dst[m][k] = *(const LAS bf16x8*)(lds + PG8_SA(b, h) + aoff + m * 2048 + k * 1024); } while (0)
; #define PG8_LDB(dst, b, h) do { _Pragma("unroll") for (int n = 0; n < 2; ++n) _Pragma("unroll") for (int k = 0; k < 2; ++k) dst[n][k] = *(const LAS bf16x8*)(lds + PG8_SB(b, h) + boff + n * 2048 + k * 1024); } while (0)
; #define PG8_SCHED __builtin_amdgcn_sched_barrier(0)
; template <class Epi, bool BSEL = false>
; __device__ __forceinline__ void gemm_phase(LAS unsigned char* lds, const Gemm g, const Order& S, const Epi& E, const int tid) {
;     ...
;         const bool has_next = S.next(ui + 1, nxt);
;         const char* nA = has_next ? nxt.a : cA; const char* nB = has_next ? nxt.b : cB;
;         const bool nP = has_next ? (BSEL && nxt.kind == 3) : cP; const size_t nhB = nP ? hstepBp : hstepBn;
;         for (int t = 0; t < nt; t += 2) {
;             const bool last = (t == nt - 2);
;             const char* a1 = cA + (size_t)(t + 1) * kstep;
;             const char* a2 = last ? nA : cA + (size_t)(t + 2) * kstep; const char* b2 = last ? nB : cB + (size_t)(t + 2) * kstep;
;             const char* a3 = a2 + kstep; const char* b3 = b2 + kstep;
;             const bool p2 = last ? nP : cP; const size_t h2 = last ? nhB : chB;
;             PG8_LDB(B0, 0, 0); PG8_LDB(B1, 0, 1); PG8_SCHED; PG8_LDA(At, 0, 0); PG8_STAGE(PG8_SA(1, 1), a1 + hstepA, voffA);
.LBB0_439:
	s_xor_b64 s[34:35], s[38:39], -1
	s_add_u32 s1, s36, 0x100
	s_addc_u32 s52, s37, 0
	s_and_b64 s[2:3], s[38:39], exec
	s_cselect_b32 s53, s29, s11
	s_cselect_b32 s54, s28, s10
	s_cselect_b32 s55, s31, s37
	s_cselect_b32 s56, s30, s36
	v_lshl_add_u64 v[160:161], s[10:11], 0, v[154:155]
	v_lshl_add_u64 v[162:163], s[10:11], 0, v[156:157]
	s_mov_b32 s57, -2
	s_mov_b64 s[2:3], 0
	.p2align 6

; #define PG8_STAGE(bufoff, gbase, voff) do { _Pragma("unroll") for (int _i = 0; _i < 2; ++_i) \
;         __builtin_amdgcn_global_load_lds((const unsigned*)((const char*)(gbase) + (voff)[_i]), (LAS unsigned*)(lds + (bufoff) + ldsw + _i * 8192), 16, 0, 0); } while (0)
; #define PG8_LDA(dst, b, h) do { _Pragma("unroll") for (int m = 0; m < 4; ++m) _Pragma("unroll") for (int k = 0; k < 2; ++k) dst[m][k] = *(const LAS bf16x8*)(lds + PG8_SA(b, h) + aoff + m * 2048 + k * 1024); } while (0)
; #define PG8_LDB(dst, b, h) do { _Pragma("unroll") for (int n = 0; n < 2; ++n) _Pragma("unroll") for (int k = 0; k < 2; ++k) dst[n][k] = *(const LAS bf16x8*)(lds + PG8_SB(b, h) + boff + n * 2048 + k * 1024); } while (0)
; #define PG8_SCHED __builtin_amdgcn_sched_barrier(0)
; template <class Epi, bool BSEL = false>
; __device__ __forceinline__ void gemm_phase(LAS unsigned char* lds, const Gemm g, const Order& S, const Epi& E, const int tid) {
;     ...
;         const bool has_next = S.next(ui + 1, nxt);
;         const char* nA = has_next ? nxt.a : cA; const char* nB = has_next ? nxt.b : cB;
;         const bool nP = has_next ? (BSEL && nxt.kind == 3) : cP; const size_t nhB = nP ? hstepBp : hstepBn;
;         for (int t = 0; t < nt; t += 2) {
;             const bool last = (t == nt - 2);
;             const char* a1 = cA + (size_t)(t + 1) * kstep;
;             const char* a2 = last ? nA : cA + (size_t)(t + 2) * kstep; const char* b2 = last ? nB : cB + (size_t)(t + 2) * kstep;
;             const char* a3 = a2 + kstep; const char* b3 = b2 + kstep;
;             const bool p2 = last ? nP : cP; const size_t h2 = last ? nhB : chB;
;             PG8_LDB(B0, 0, 0); PG8_LDB(B1, 0, 1); PG8_SCHED; PG8_LDA(At, 0, 0); PG8_STAGE(PG8_SA(1, 1), a1 + hstepA, voffA);
.LBB0_471:
	s_xor_b64 s[42:43], s[2:3], -1
	s_add_u32 s41, s46, 0x100
	s_addc_u32 s57, s47, 0
	s_and_b64 s[44:45], s[2:3], exec
	s_cselect_b32 s58, s37, s27
	s_cselect_b32 s59, s36, s26
	s_cselect_b32 s62, s39, s47
	s_cselect_b32 s63, s38, s46
	v_lshl_add_u64 v[146:147], s[26:27], 0, v[140:141]
	v_lshl_add_u64 v[148:149], s[26:27], 0, v[142:143]
	s_mov_b32 s64, -2
	s_mov_b64 s[44:45], 0
	.p2align 6

; template <class Epi, bool BSEL = false>
; __device__ __forceinline__ void gemm_phase(LAS unsigned char* lds, const Gemm g, const Order& S, const Epi& E, const int tid) {
;     ...
;     for (;;) {
;         const bool has_next = S.next(ui + 1, nxt);
;         const char* nA = has_next ? nxt.a : cA; const char* nB = has_next ? nxt.b : cB;
;         const bool nP = has_next ? (BSEL && nxt.kind == 3) : cP; const size_t nhB = nP ? hstepBp : hstepBn;
;         for (int t = 0; t < nt; t += 2) {
.LBB0_657:
	s_mov_b64 s[0:1], 0
	.p2align 6

; #define PG8_STAGE(bufoff, gbase, voff) do { _Pragma("unroll") for (int _i = 0; _i < 2; ++_i) \
;         __builtin_amdgcn_global_load_lds((const unsigned*)((const char*)(gbase) + (voff)[_i]), (LAS unsigned*)(lds + (bufoff) + ldsw + _i * 8192), 16, 0, 0); } while (0)
; #define PG8_LDA(dst, b, h) do { _Pragma("unroll") for (int m = 0; m < 4; ++m) _Pragma("unroll") for (int k = 0; k < 2; ++k) dst[m][k] = *(const LAS bf16x8*)(lds + PG8_SA(b, h) + aoff + m * 2048 + k * 1024); } while (0)
; #define PG8_LDB(dst, b, h) do { _Pragma("unroll") for (int n = 0; n < 2; ++n) _Pragma("unroll") for (int k = 0; k < 2; ++k) dst[n][k] = *(const LAS bf16x8*)(lds + PG8_SB(b, h) + boff + n * 2048 + k * 1024); } while (0)
; #define PG8_SCHED __builtin_amdgcn_sched_barrier(0)
; template <class Epi, bool BSEL = false>
; __device__ __forceinline__ void gemm_phase(LAS unsigned char* lds, const Gemm g, const Order& S, const Epi& E, const int tid) {
;     ...
;         const bool has_next = S.next(ui + 1, nxt);
;         const char* nA = has_next ? nxt.a : cA; const char* nB = has_next ? nxt.b : cB;
;         const bool nP = has_next ? (BSEL && nxt.kind == 3) : cP; const size_t nhB = nP ? hstepBp : hstepBn;
;         for (int t = 0; t < nt; t += 2) {
;             const bool last = (t == nt - 2);
;             const char* a1 = cA + (size_t)(t + 1) * kstep;
;             const char* a2 = last ? nA : cA + (size_t)(t + 2) * kstep; const char* b2 = last ? nB : cB + (size_t)(t + 2) * kstep;
;             const char* a3 = a2 + kstep; const char* b3 = b2 + kstep;
;             const bool p2 = last ? nP : cP; const size_t h2 = last ? nhB : chB;
;             PG8_LDB(B0, 0, 0); PG8_LDB(B1, 0, 1); PG8_SCHED; PG8_LDA(At, 0, 0); PG8_STAGE(PG8_SA(1, 1), a1 + hstepA, voffA);
.LBB0_668:
	s_mov_b64 s[6:7], 0
	.p2align 6
.LBB0_669:
	s_xor_b64 s[54:55], s[6:7], -1
	s_add_u32 s15, s8, 0x100
	s_addc_u32 s47, s9, 0
	s_and_b64 s[2:3], s[6:7], exec
	s_cselect_b32 s58, s49, s27
	s_cselect_b32 s59, s48, s26
	s_cselect_b32 s64, s53, s9
	s_cselect_b32 s65, s52, s8
	s_cmp_eq_u32 s12, 3
	s_cselect_b64 s[56:57], -1, 0
	v_cndmask_b32_e64 v128, 0, 1, s[56:57]
	v_cndmask_b32_e64 v132, 0, 1, s[42:43]
	v_cndmask_b32_e64 v128, v132, v128, s[6:7]
	v_and_b32_e32 v128, 1, v128
	v_cmp_eq_u32_e32 vcc, 1, v128
	s_and_b64 s[2:3], vcc, exec
	s_cselect_b32 s28, s75, 0x40000
	s_mov_b64 s[60:61], s[28:29]
	s_waitcnt lgkmcnt(0)
	v_lshl_add_u64 v[128:129], s[26:27], 0, v[172:173]
	v_lshl_add_u64 v[130:131], s[26:27], 0, v[174:175]
	s_mov_b32 s95, -2
	s_mov_b64 s[62:63], 0
	.p2align 6

;     __device__ __forceinline__ bool next(int i, Unit& u) const {
;         const long L = (long)i * G + c; if (L >= total) return false;
;         int w = (int)L; { const int q = total / 8, r = total % 8, xcd = w % 8, off = w / 8; w = (xcd < r ? xcd * (q + 1) : r * (q + 1) + (xcd - r) * q) + off; }
.LBB0_824:
	s_ashr_i32 s2, s35, 3
	s_add_i32 s2, s39, s2
	s_cmpk_gt_i32 s2, 0xff
	s_cbranch_scc1 .LBB0_826
	.p2align 6

.Lst0_loop:
	s_cmp_lg_u32 s41, 0
	s_cbranch_scc1 .Lst0_single
	s_and_b32 s2, s20, 0xffff
	s_cmp_lg_u32 s2, 0xc000
	s_cbranch_scc1 .Lst0_single
	s_cmp_lt_u32 s21, 50
	s_cbranch_scc1 .Lst0_u6
	.p2align 6

.Lst0_u6:
	v_add_u32_e32 v236, 0x10000, v206
	v_add_u32_e32 v237, 0x10000, v207
	v_add_u32_e32 v238, 0x10000, v208
	v_add_u32_e32 v239, 0x10000, v209
	.p2align 6

.Lst1_loop:
	s_cmp_lg_u32 s48, 1
	s_cbranch_scc1 .Lst1_single
	s_and_b32 s2, s46, 0xffff
	s_cmp_lg_u32 s2, 0x0
	s_cbranch_scc1 .Lst1_single
	s_cmp_lt_u32 s47, 50
	s_cbranch_scc1 .Lst1_u6
	.p2align 6

;     __device__ __forceinline__ bool next(int i, Unit& u) const {
;         const long L = (long)i * G + c; if (L >= total) return false;
;         int w = (int)L; { const int q = total / 8, r = total % 8, xcd = w % 8, off = w / 8; w = (xcd < r ? xcd * (q + 1) : r * (q + 1) + (xcd - r) * q) + off; }
.LBB0_1069:
	s_ashr_i32 s1, s1, 3
	s_add_i32 s1, s30, s1
	s_cmpk_gt_i32 s1, 0xff
	s_cbranch_scc1 .LBB0_1071
	.p2align 6

; #define PG8_STAGE(bufoff, gbase, voff) do { _Pragma("unroll") for (int _i = 0; _i < 2; ++_i) \
;         __builtin_amdgcn_global_load_lds((const unsigned*)((const char*)(gbase) + (voff)[_i]), (LAS unsigned*)(lds + (bufoff) + ldsw + _i * 8192), 16, 0, 0); } while (0)
; #define PG8_LDA(dst, b, h) do { _Pragma("unroll") for (int m = 0; m < 4; ++m) _Pragma("unroll") for (int k = 0; k < 2; ++k) dst[m][k] = *(const LAS bf16x8*)(lds + PG8_SA(b, h) + aoff + m * 2048 + k * 1024); } while (0)
; #define PG8_LDB(dst, b, h) do { _Pragma("unroll") for (int n = 0; n < 2; ++n) _Pragma("unroll") for (int k = 0; k < 2; ++k) dst[n][k] = *(const LAS bf16x8*)(lds + PG8_SB(b, h) + boff + n * 2048 + k * 1024); } while (0)
; #define PG8_SCHED __builtin_amdgcn_sched_barrier(0)
; template <class Epi, bool BSEL = false>
; __device__ __forceinline__ void gemm_phase(LAS unsigned char* lds, const Gemm g, const Order& S, const Epi& E, const int tid) {
;     ...
;         const bool has_next = S.next(ui + 1, nxt);
;         const char* nA = has_next ? nxt.a : cA; const char* nB = has_next ? nxt.b : cB;
;         const bool nP = has_next ? (BSEL && nxt.kind == 3) : cP; const size_t nhB = nP ? hstepBp : hstepBn;
;         for (int t = 0; t < nt; t += 2) {
;             const bool last = (t == nt - 2);
;             const char* a1 = cA + (size_t)(t + 1) * kstep;
;             const char* a2 = last ? nA : cA + (size_t)(t + 2) * kstep; const char* b2 = last ? nB : cB + (size_t)(t + 2) * kstep;
;             const char* a3 = a2 + kstep; const char* b3 = b2 + kstep;
;             const bool p2 = last ? nP : cP; const size_t h2 = last ? nhB : chB;
;             PG8_LDB(B0, 0, 0); PG8_LDB(B1, 0, 1); PG8_SCHED; PG8_LDA(At, 0, 0); PG8_STAGE(PG8_SA(1, 1), a1 + hstepA, voffA);
.LBB0_1071:
	s_xor_b64 s[30:31], s[36:37], -1
	s_add_u32 s1, s34, 0x100
	s_addc_u32 s25, s35, 0
	s_and_b64 s[2:3], s[36:37], exec
	s_cselect_b32 s52, s27, s7
	s_cselect_b32 s53, s26, s6
	s_cselect_b32 s54, s29, s35
	s_cselect_b32 s55, s28, s34
	s_waitcnt lgkmcnt(0)
	v_lshl_add_u64 v[128:129], s[6:7], 0, v[166:167]
	v_lshl_add_u64 v[130:131], s[6:7], 0, v[168:169]
	s_mov_b32 s56, -2
	s_mov_b64 s[2:3], 0
	.p2align 6

; #define PG8_STAGE(bufoff, gbase, voff) do { _Pragma("unroll") for (int _i = 0; _i < 2; ++_i) \
;         __builtin_amdgcn_global_load_lds((const unsigned*)((const char*)(gbase) + (voff)[_i]), (LAS unsigned*)(lds + (bufoff) + ldsw + _i * 8192), 16, 0, 0); } while (0)
; #define PG8_LDA(dst, b, h) do { _Pragma("unroll") for (int m = 0; m < 4; ++m) _Pragma("unroll") for (int k = 0; k < 2; ++k) dst[m][k] = *(const LAS bf16x8*)(lds + PG8_SA(b, h) + aoff + m * 2048 + k * 1024); } while (0)
; #define PG8_LDB(dst, b, h) do { _Pragma("unroll") for (int n = 0; n < 2; ++n) _Pragma("unroll") for (int k = 0; k < 2; ++k) dst[n][k] = *(const LAS bf16x8*)(lds + PG8_SB(b, h) + boff + n * 2048 + k * 1024); } while (0)
; #define PG8_SCHED __builtin_amdgcn_sched_barrier(0)
; template <class Epi, bool BSEL = false>
; __device__ __forceinline__ void gemm_phase(LAS unsigned char* lds, const Gemm g, const Order& S, const Epi& E, const int tid) {
;     ...
;         const bool has_next = S.next(ui + 1, nxt);
;         const char* nA = has_next ? nxt.a : cA; const char* nB = has_next ? nxt.b : cB;
;         const bool nP = has_next ? (BSEL && nxt.kind == 3) : cP; const size_t nhB = nP ? hstepBp : hstepBn;
;         for (int t = 0; t < nt; t += 2) {
;             const bool last = (t == nt - 2);
;             const char* a1 = cA + (size_t)(t + 1) * kstep;
;             const char* a2 = last ? nA : cA + (size_t)(t + 2) * kstep; const char* b2 = last ? nB : cB + (size_t)(t + 2) * kstep;
;             const char* a3 = a2 + kstep; const char* b3 = b2 + kstep;
;             const bool p2 = last ? nP : cP; const size_t h2 = last ? nhB : chB;
;             PG8_LDB(B0, 0, 0); PG8_LDB(B1, 0, 1); PG8_SCHED; PG8_LDA(At, 0, 0); PG8_STAGE(PG8_SA(1, 1), a1 + hstepA, voffA);
.LBB0_1100:
	s_xor_b64 s[36:37], s[2:3], -1
	s_add_u32 s27, s38, 0x100
	s_addc_u32 s35, s39, 0
	s_and_b64 s[40:41], s[2:3], exec
	s_cselect_b32 s51, s29, s9
	s_cselect_b32 s52, s28, s8
	s_cselect_b32 s53, s31, s39
	s_cselect_b32 s54, s30, s38
	v_lshl_add_u64 v[146:147], s[8:9], 0, v[138:139]
	v_lshl_add_u64 v[148:149], s[8:9], 0, v[140:141]
	s_mov_b32 s55, -2
	s_mov_b64 s[38:39], 0
	.p2align 6

; #define PG8_STAGE(bufoff, gbase, voff) do { _Pragma("unroll") for (int _i = 0; _i < 2; ++_i) \
;         __builtin_amdgcn_global_load_lds((const unsigned*)((const char*)(gbase) + (voff)[_i]), (LAS unsigned*)(lds + (bufoff) + ldsw + _i * 8192), 16, 0, 0); } while (0)
; #define PG8_LDA(dst, b, h) do { _Pragma("unroll") for (int m = 0; m < 4; ++m) _Pragma("unroll") for (int k = 0; k < 2; ++k) dst[m][k] = *(const LAS bf16x8*)(lds + PG8_SA(b, h) + aoff + m * 2048 + k * 1024); } while (0)
; #define PG8_LDB(dst, b, h) do { _Pragma("unroll") for (int n = 0; n < 2; ++n) _Pragma("unroll") for (int k = 0; k < 2; ++k) dst[n][k] = *(const LAS bf16x8*)(lds + PG8_SB(b, h) + boff + n * 2048 + k * 1024); } while (0)
; #define PG8_SCHED __builtin_amdgcn_sched_barrier(0)
; template <class Epi, bool BSEL = false>
; __device__ __forceinline__ void gemm_phase(LAS unsigned char* lds, const Gemm g, const Order& S, const Epi& E, const int tid) {
;     ...
;         const bool has_next = S.next(ui + 1, nxt);
;         const char* nA = has_next ? nxt.a : cA; const char* nB = has_next ? nxt.b : cB;
;         const bool nP = has_next ? (BSEL && nxt.kind == 3) : cP; const size_t nhB = nP ? hstepBp : hstepBn;
;         for (int t = 0; t < nt; t += 2) {
;             const bool last = (t == nt - 2);
;             const char* a1 = cA + (size_t)(t + 1) * kstep;
;             const char* a2 = last ? nA : cA + (size_t)(t + 2) * kstep; const char* b2 = last ? nB : cB + (size_t)(t + 2) * kstep;
;             const char* a3 = a2 + kstep; const char* b3 = b2 + kstep;
;             const bool p2 = last ? nP : cP; const size_t h2 = last ? nhB : chB;
;             PG8_LDB(B0, 0, 0); PG8_LDB(B1, 0, 1); PG8_SCHED; PG8_LDA(At, 0, 0); PG8_STAGE(PG8_SA(1, 1), a1 + hstepA, voffA);
.LBB0_1270:
	s_xor_b64 s[34:35], s[38:39], -1
	s_add_u32 s27, s36, 0x100
	s_addc_u32 s51, s37, 0
	s_and_b64 s[2:3], s[38:39], exec
	s_cselect_b32 s52, s29, s9
	s_cselect_b32 s53, s28, s8
	s_cselect_b32 s54, s31, s37
	s_cselect_b32 s55, s30, s36
	v_lshl_add_u64 v[142:143], s[8:9], 0, v[136:137]
	v_lshl_add_u64 v[144:145], s[8:9], 0, v[138:139]
	s_mov_b32 s56, -2
	.p2align 6

;     __device__ __forceinline__ bool next(int i, Unit& u) const {
;         const long L = (long)i * G + c; if (L >= total) return false;
;         int w = (int)L; { const int q = total / 8, r = total % 8, xcd = w % 8, off = w / 8; w = (xcd < r ? xcd * (q + 1) : r * (q + 1) + (xcd - r) * q) + off; }
.LBB0_1361:
	s_ashr_i32 s1, s1, 3
	s_add_i32 s1, s27, s1
	s_cmpk_gt_i32 s1, 0xff
	s_cbranch_scc1 .LBB0_1363
	.p2align 6

; #define PG8_STAGE(bufoff, gbase, voff) do { _Pragma("unroll") for (int _i = 0; _i < 2; ++_i) \
;         __builtin_amdgcn_global_load_lds((const unsigned*)((const char*)(gbase) + (voff)[_i]), (LAS unsigned*)(lds + (bufoff) + ldsw + _i * 8192), 16, 0, 0); } while (0)
; #define PG8_LDA(dst, b, h) do { _Pragma("unroll") for (int m = 0; m < 4; ++m) _Pragma("unroll") for (int k = 0; k < 2; ++k) dst[m][k] = *(const LAS bf16x8*)(lds + PG8_SA(b, h) + aoff + m * 2048 + k * 1024); } while (0)
; #define PG8_LDB(dst, b, h) do { _Pragma("unroll") for (int n = 0; n < 2; ++n) _Pragma("unroll") for (int k = 0; k < 2; ++k) dst[n][k] = *(const LAS bf16x8*)(lds + PG8_SB(b, h) + boff + n * 2048 + k * 1024); } while (0)
; #define PG8_SCHED __builtin_amdgcn_sched_barrier(0)
; template <class Epi, bool BSEL = false>
; __device__ __forceinline__ void gemm_phase(LAS unsigned char* lds, const Gemm g, const Order& S, const Epi& E, const int tid) {
;     ...
;         const bool has_next = S.next(ui + 1, nxt);
;         const char* nA = has_next ? nxt.a : cA; const char* nB = has_next ? nxt.b : cB;
;         const bool nP = has_next ? (BSEL && nxt.kind == 3) : cP; const size_t nhB = nP ? hstepBp : hstepBn;
;         for (int t = 0; t < nt; t += 2) {
;             const bool last = (t == nt - 2);
;             const char* a1 = cA + (size_t)(t + 1) * kstep;
;             const char* a2 = last ? nA : cA + (size_t)(t + 2) * kstep; const char* b2 = last ? nB : cB + (size_t)(t + 2) * kstep;
;             const char* a3 = a2 + kstep; const char* b3 = b2 + kstep;
;             const bool p2 = last ? nP : cP; const size_t h2 = last ? nhB : chB;
;             PG8_LDB(B0, 0, 0); PG8_LDB(B1, 0, 1); PG8_SCHED; PG8_LDA(At, 0, 0); PG8_STAGE(PG8_SA(1, 1), a1 + hstepA, voffA);
.LBB0_1363:
	s_xor_b64 s[26:27], s[30:31], -1
	s_add_u32 s1, s28, 0x100
	s_addc_u32 s49, s29, 0
	s_and_b64 s[2:3], s[30:31], exec
	s_cselect_b32 s50, s23, s7
	s_cselect_b32 s51, s22, s6
	s_cselect_b32 s52, s25, s29
	s_cselect_b32 s53, s24, s28
	v_lshl_add_u64 v[156:157], s[6:7], 0, v[150:151]
	v_lshl_add_u64 v[158:159], s[6:7], 0, v[152:153]
	s_mov_b32 s54, -2
	s_mov_b64 s[2:3], 0
	.p2align 6

; #define PG8_STAGE(bufoff, gbase, voff) do { _Pragma("unroll") for (int _i = 0; _i < 2; ++_i) \
;         __builtin_amdgcn_global_load_lds((const unsigned*)((const char*)(gbase) + (voff)[_i]), (LAS unsigned*)(lds + (bufoff) + ldsw + _i * 8192), 16, 0, 0); } while (0)
; #define PG8_LDA(dst, b, h) do { _Pragma("unroll") for (int m = 0; m < 4; ++m) _Pragma("unroll") for (int k = 0; k < 2; ++k) dst[m][k] = *(const LAS bf16x8*)(lds + PG8_SA(b, h) + aoff + m * 2048 + k * 1024); } while (0)
; #define PG8_LDB(dst, b, h) do { _Pragma("unroll") for (int n = 0; n < 2; ++n) _Pragma("unroll") for (int k = 0; k < 2; ++k) dst[n][k] = *(const LAS bf16x8*)(lds + PG8_SB(b, h) + boff + n * 2048 + k * 1024); } while (0)
; #define PG8_SCHED __builtin_amdgcn_sched_barrier(0)
; template <class Epi, bool BSEL = false>
; __device__ __forceinline__ void gemm_phase(LAS unsigned char* lds, const Gemm g, const Order& S, const Epi& E, const int tid) {
;     ...
;         const bool has_next = S.next(ui + 1, nxt);
;         const char* nA = has_next ? nxt.a : cA; const char* nB = has_next ? nxt.b : cB;
;         const bool nP = has_next ? (BSEL && nxt.kind == 3) : cP; const size_t nhB = nP ? hstepBp : hstepBn;
;         for (int t = 0; t < nt; t += 2) {
;             const bool last = (t == nt - 2);
;             const char* a1 = cA + (size_t)(t + 1) * kstep;
;             const char* a2 = last ? nA : cA + (size_t)(t + 2) * kstep; const char* b2 = last ? nB : cB + (size_t)(t + 2) * kstep;
;             const char* a3 = a2 + kstep; const char* b3 = b2 + kstep;
;             const bool p2 = last ? nP : cP; const size_t h2 = last ? nhB : chB;
;             PG8_LDB(B0, 0, 0); PG8_LDB(B1, 0, 1); PG8_SCHED; PG8_LDA(At, 0, 0); PG8_STAGE(PG8_SA(1, 1), a1 + hstepA, voffA);
.LBB0_1392:
	s_xor_b64 s[30:31], s[2:3], -1
	s_add_u32 s29, s34, 0x100
	s_addc_u32 s48, s35, 0
	s_and_b64 s[36:37], s[2:3], exec
	s_cselect_b32 s49, s25, s9
	s_cselect_b32 s50, s24, s8
	s_cselect_b32 s51, s27, s35
	s_cselect_b32 s52, s26, s34
	v_lshl_add_u64 v[146:147], s[8:9], 0, v[140:141]
	v_lshl_add_u64 v[148:149], s[8:9], 0, v[142:143]
	s_mov_b32 s53, -2
	s_mov_b64 s[34:35], 0
	.p2align 6
